# v21: v19 + all four hgrn_item load blocks (P2 pass 1, P5 pass 3; first and next sub-chunk) issue their 2-byte loads back to back
# speedup vs baseline: 1.0097x; 1.0061x over previous
; #define LAS __attribute__((address_space(3)))
; template <bool OUT> DI void hgrn_item(LAS unsigned char* lds, bf16_t* proj, float* hst, float* hdv, const float* normw, int item, bool dry) {
;     ...
;     if (OUT) {
; #pragma unroll
;         for (int i = 0; i < 8; ++i) st[i] = *(const f32x4*)(hs + i * 256);
;     } else {
; #pragma unroll
;         for (int i = 0; i < 8; ++i) st[i] = (f32x4){0.f, 0.f, 0.f, 0.f};
;     }
;     float btot = 0.f;
;     unsigned rg[8], rqv[8], rvv[8];
;     ...
;     HG_LOAD(0);
;     ...
;         *(LAS u32x4*)(VT + d * TP + tq * 16) = (u32x4){rvv[0], rvv[1], rvv[2], rvv[3]};
;         *(LAS u32x4*)(VT + d * TP + tq * 16 + 8) = (u32x4){rvv[4], rvv[5], rvv[6], rvv[7]};
.LBB0_825:
	s_ashr_i32 s36, s34, 6
	s_ashr_i32 s37, s36, 31
	s_lshl_b32 s30, s34, 8
	s_lshl_b64 s[38:39], s[36:37], 12
	s_and_b32 s30, s30, 0xf00
	s_or_b32 s30, s38, s30
	v_or_b32_e32 v2, s30, v48
	v_mad_u64_u32 v[2:3], s[86:87], v2, s47, v[54:55]
	s_lshl_b32 s30, s34, 4
	v_mad_i32_i24 v3, s39, v68, v3
	s_and_b32 s30, s30, 0x300
	v_lshl_add_u64 v[2:3], v[2:3], 0, s[30:31]
	v_lshl_add_u64 v[2:3], v[2:3], 0, v[42:43]
	v_add_co_u32_e32 v4, vcc, s50, v2
	s_bfe_u32 s30, s40, 0x40008
	s_nop 0
	v_addc_co_u32_e32 v5, vcc, 0, v3, vcc
	v_add_co_u32_e32 v6, vcc, s51, v2
	s_mul_i32 s35, s30, 0x320000
	s_nop 0
	v_addc_co_u32_e32 v7, vcc, 0, v3, vcc
	v_add_co_u32_e32 v8, vcc, s52, v2
	s_lshl_b32 s30, s84, 1
	s_nop 0
	v_addc_co_u32_e32 v9, vcc, 0, v3, vcc
	v_add_co_u32_e32 v10, vcc, s53, v2
	s_and_b32 s38, s30, 0x300
	s_nop 0
	v_addc_co_u32_e32 v11, vcc, 0, v3, vcc
	v_add_co_u32_e32 v12, vcc, s54, v2
	v_readfirstlane_b32 s30, v183
	s_nop 0
	v_addc_co_u32_e32 v13, vcc, 0, v3, vcc
	global_load_ushort v130, v[2:3], off offset:2560
	global_load_ushort v131, v[4:5], off offset:3072
	global_load_ushort v132, v[6:7], off
	global_load_ushort v133, v[8:9], off offset:3584
	global_load_ushort v134, v[10:11], off
	global_load_ushort v135, v[12:13], off offset:512
	global_load_ushort v136, v[10:11], off offset:1024
	global_load_ushort v137, v[2:3], off offset:3584
	v_add_co_u32_e32 v4, vcc, s55, v2
	s_lshr_b32 s30, s30, 6
	s_nop 0
	v_addc_co_u32_e32 v5, vcc, 0, v3, vcc
	v_add_co_u32_e32 v6, vcc, s58, v2
	s_mul_hi_i32 s37, s36, 0x3200000
	s_nop 0
	v_addc_co_u32_e32 v7, vcc, 0, v3, vcc
	v_add_co_u32_e32 v8, vcc, s59, v2
	s_mul_i32 s36, s36, 0x3200000
	s_nop 0
	v_addc_co_u32_e32 v9, vcc, 0, v3, vcc
	v_add_co_u32_e32 v10, vcc, s72, v2
	s_add_u32 s35, s36, s35
	s_nop 0
	v_addc_co_u32_e32 v11, vcc, 0, v3, vcc
	global_load_ushort v138, v[4:5], off offset:512
	global_load_ushort v139, v[6:7], off offset:1024
	global_load_ushort v140, v[6:7], off offset:2048
	global_load_ushort v141, v[8:9], off offset:1536
	global_load_ushort v142, v[10:11], off offset:2048
	global_load_ushort v143, v[10:11], off offset:3072
	global_load_ushort v144, v[8:9], off offset:2560
	global_load_ushort v145, v[4:5], off offset:1536
	v_add_co_u32_e32 v4, vcc, s73, v2
	s_addc_u32 s37, s37, 0
	s_nop 0
	v_addc_co_u32_e32 v5, vcc, 0, v3, vcc
	v_add_co_u32_e32 v6, vcc, s74, v2
	s_or_b32 s36, s35, s38
	s_nop 0
	v_addc_co_u32_e32 v7, vcc, 0, v3, vcc
	v_add_co_u32_e32 v8, vcc, s75, v2
	v_lshl_add_u64 v[56:57], v[52:53], 0, s[36:37]
	s_nop 0
	v_addc_co_u32_e32 v9, vcc, 0, v3, vcc
	v_add_co_u32_e32 v10, vcc, s76, v2
	s_mov_b64 s[36:37], 0
	s_nop 0
	v_addc_co_u32_e32 v11, vcc, 0, v3, vcc
	v_add_co_u32_e32 v12, vcc, s77, v2
	v_mov_b32_e32 v70, 0
	s_nop 0
	v_addc_co_u32_e32 v13, vcc, 0, v3, vcc
	v_add_co_u32_e32 v14, vcc, s78, v2
	v_addc_co_u32_e32 v15, vcc, 0, v3, vcc
	global_load_ushort v146, v[4:5], off offset:2560
	global_load_ushort v147, v[6:7], off offset:3072
	global_load_ushort v148, v[8:9], off
	s_nop 0
	global_load_ushort v149, v[10:11], off offset:3584
	s_nop 0
	global_load_ushort v150, v[12:13], off
	s_nop 0
	global_load_ushort v151, v[14:15], off offset:512
	s_nop 0
	global_load_ushort v152, v[12:13], off offset:1024
	s_nop 0
	global_load_ushort v153, v[4:5], off offset:3584
	v_add_co_u32_e32 v4, vcc, s79, v2
	s_nop 0
	v_addc_co_u32_e32 v5, vcc, 0, v3, vcc
	v_add_co_u32_e32 v6, vcc, s80, v2
	s_nop 0
	v_addc_co_u32_e32 v7, vcc, 0, v3, vcc
	v_add_co_u32_e32 v8, vcc, s81, v2
	s_nop 0
	v_addc_co_u32_e32 v9, vcc, 0, v3, vcc
	v_add_co_u32_e32 v2, vcc, s82, v2
	s_nop 0
	v_addc_co_u32_e32 v3, vcc, 0, v3, vcc
	global_load_ushort v154, v[4:5], off offset:512
	global_load_ushort v155, v[6:7], off offset:1024
	s_nop 0
	global_load_ushort v156, v[6:7], off offset:2048
	s_nop 0
	global_load_ushort v157, v[8:9], off offset:1536
	global_load_ushort v158, v[2:3], off offset:3072
	s_nop 0
	global_load_ushort v159, v[8:9], off offset:2560
	s_nop 0
	global_load_ushort v160, v[4:5], off offset:1536
	s_nop 0
	global_load_ushort v161, v[2:3], off offset:2048
	v_mov_b32_e32 v30, 0
	v_mov_b32_e32 v31, v47
	v_mov_b32_e32 v26, 0
	v_mov_b32_e32 v27, v47
	v_mov_b32_e32 v28, v47
	v_mov_b32_e32 v29, v47
	v_mov_b32_e32 v22, 0
	v_mov_b32_e32 v23, v47
	v_mov_b32_e32 v24, v47
	v_mov_b32_e32 v25, v47
	v_mov_b32_e32 v18, 0
	v_mov_b32_e32 v19, v47
	v_mov_b32_e32 v20, v47
	v_mov_b32_e32 v21, v47
	v_mov_b32_e32 v16, v47
	v_mov_b32_e32 v17, v47
	v_mov_b32_e32 v3, v47
	v_mov_b32_e32 v5, v47
	v_mov_b32_e32 v9, v47
	v_mov_b32_e32 v32, v47
	v_mov_b32_e32 v33, v47
	v_mov_b32_e32 v10, 0
	v_mov_b32_e32 v14, 0
	v_mov_b32_e32 v11, v47
	v_mov_b32_e32 v12, v47
	v_mov_b32_e32 v13, v47
	v_mov_b32_e32 v15, v47
	v_lshl_or_b32 v2, s30, 4, v62
	v_mul_lo_u32 v2, v2, s33
	v_add_u32_e32 v71, v66, v2
	v_mov_b32_e32 v2, 0
	v_mov_b32_e32 v4, v47
	v_mov_b32_e32 v6, 0
	v_mov_b32_e32 v7, v47
	v_mov_b32_e32 v8, v47
	s_cmp_eq_u32 s36, 0x258000
	s_waitcnt vmcnt(30)
	v_lshl_or_b32 v58, v131, 16, v130
	s_waitcnt vmcnt(27)
	v_lshl_or_b32 v59, v134, 16, v133
	s_waitcnt vmcnt(24)
	v_lshl_or_b32 v34, v132, 16, v137
	v_lshl_or_b32 v35, v136, 16, v135
	s_waitcnt vmcnt(22)
	v_lshl_or_b32 v60, v139, 16, v138
	s_waitcnt vmcnt(19)
	v_lshl_or_b32 v61, v142, 16, v141
	s_waitcnt vmcnt(17)
	v_lshl_or_b32 v37, v143, 16, v144
	s_waitcnt vmcnt(16)
	v_lshl_or_b32 v36, v140, 16, v145
	v_mov_b32_e32 v72, v58
	v_mov_b32_e32 v73, v59
	v_mov_b32_e32 v74, v60
	v_mov_b32_e32 v75, v61
	s_waitcnt vmcnt(14)
	v_lshl_or_b32 v80, v147, 16, v146
	s_waitcnt vmcnt(11)
	v_lshl_or_b32 v81, v150, 16, v149
	s_waitcnt vmcnt(9)
	v_lshl_or_b32 v39, v152, 16, v151
	s_waitcnt vmcnt(8)
	v_lshl_or_b32 v38, v148, 16, v153
	v_mov_b32_e32 v76, v80
	v_mov_b32_e32 v77, v81
	s_waitcnt vmcnt(6)
	v_lshl_or_b32 v82, v155, 16, v154
	v_mov_b32_e32 v78, v82
	s_waitcnt vmcnt(2)
	v_lshl_or_b32 v41, v158, 16, v159
	s_waitcnt vmcnt(1)
	v_lshl_or_b32 v40, v156, 16, v160
	s_waitcnt vmcnt(0)
	v_lshl_or_b32 v83, v161, 16, v157
	v_mov_b32_e32 v79, v83
	ds_write_b128 v63, v[34:37] offset:53248
	ds_write_b128 v63, v[38:41] offset:53264
	s_cbranch_scc1 .LBB0_827
; template <bool OUT> DI void hgrn_item(LAS unsigned char* lds, bf16_t* proj, float* hst, float* hdv, const float* normw, int item, bool dry) {
;     ...
;         if (sc < 3) HG_LOAD(sc + 1);
.LBB0_826:
	v_lshl_add_u64 v[34:35], v[56:57], 0, s[36:37]
	v_add_co_u32_e32 v36, vcc, 0xc8000, v34
	s_nop 1
	v_addc_co_u32_e32 v37, vcc, 0, v35, vcc
	v_add_co_u32_e32 v38, vcc, 0xcb000, v34
	s_nop 1
	v_addc_co_u32_e32 v39, vcc, 0, v35, vcc
	v_add_co_u32_e32 v40, vcc, 0xcc000, v34
	s_nop 1
	v_addc_co_u32_e32 v41, vcc, 0, v35, vcc
	v_add_co_u32_e32 v72, vcc, 0xce000, v34
	s_nop 1
	v_addc_co_u32_e32 v73, vcc, 0, v35, vcc
	v_add_co_u32_e32 v74, vcc, 0xd2000, v34
	s_nop 1
	v_addc_co_u32_e32 v75, vcc, 0, v35, vcc
	v_add_co_u32_e32 v76, vcc, 0xcf000, v34
	s_nop 1
	v_addc_co_u32_e32 v77, vcc, 0, v35, vcc
	global_load_ushort v78, v[36:37], off offset:2560
	global_load_ushort v79, v[38:39], off offset:3072
	global_load_ushort v84, v[40:41], off
	global_load_ushort v85, v[72:73], off offset:3584
	global_load_ushort v86, v[74:75], off
	global_load_ushort v87, v[76:77], off offset:512
	global_load_ushort v88, v[74:75], off offset:1024
	global_load_ushort v89, v[36:37], off offset:3584
	v_add_co_u32_e32 v36, vcc, 0xd5000, v34
	s_nop 1
	v_addc_co_u32_e32 v37, vcc, 0, v35, vcc
	v_add_co_u32_e32 v38, vcc, 0xd8000, v34
	s_nop 1
	v_addc_co_u32_e32 v39, vcc, 0, v35, vcc
	v_add_co_u32_e32 v40, vcc, 0xdb000, v34
	s_nop 1
	v_addc_co_u32_e32 v41, vcc, 0, v35, vcc
	v_add_co_u32_e32 v72, vcc, 0xde000, v34
	s_nop 1
	v_addc_co_u32_e32 v73, vcc, 0, v35, vcc
	global_load_ushort v90, v[36:37], off offset:512
	global_load_ushort v91, v[38:39], off offset:1024
	global_load_ushort v92, v[38:39], off offset:2048
	global_load_ushort v93, v[40:41], off offset:1536
	global_load_ushort v94, v[72:73], off offset:2048
	global_load_ushort v95, v[72:73], off offset:3072
	global_load_ushort v96, v[40:41], off offset:2560
	global_load_ushort v97, v[36:37], off offset:1536
	v_add_co_u32_e32 v36, vcc, 0xe1000, v34
	s_nop 1
	v_addc_co_u32_e32 v37, vcc, 0, v35, vcc
	v_add_co_u32_e32 v38, vcc, 0xe4000, v34
	s_nop 1
	v_addc_co_u32_e32 v39, vcc, 0, v35, vcc
	v_add_co_u32_e32 v40, vcc, 0xe5000, v34
	s_nop 1
	v_addc_co_u32_e32 v41, vcc, 0, v35, vcc
	v_add_co_u32_e32 v72, vcc, 0xe7000, v34
	s_nop 1
	v_addc_co_u32_e32 v73, vcc, 0, v35, vcc
	v_add_co_u32_e32 v74, vcc, 0xeb000, v34
	s_nop 1
	v_addc_co_u32_e32 v75, vcc, 0, v35, vcc
	v_add_co_u32_e32 v76, vcc, 0xe8000, v34
	s_nop 1
	v_addc_co_u32_e32 v77, vcc, 0, v35, vcc
	global_load_ushort v98, v[36:37], off offset:2560
	global_load_ushort v99, v[38:39], off offset:3072
	global_load_ushort v100, v[40:41], off
	global_load_ushort v101, v[72:73], off offset:3584
	global_load_ushort v102, v[74:75], off
	global_load_ushort v103, v[76:77], off offset:512
	global_load_ushort v104, v[74:75], off offset:1024
	s_nop 0
	global_load_ushort v77, v[36:37], off offset:3584
	v_add_co_u32_e32 v36, vcc, 0xee000, v34
	v_addc_co_u32_e32 v37, vcc, 0, v35, vcc
	v_add_co_u32_e32 v38, vcc, 0xf1000, v34
	v_addc_co_u32_e32 v39, vcc, 0, v35, vcc
	v_add_co_u32_e32 v40, vcc, 0xf4000, v34
	v_addc_co_u32_e32 v41, vcc, 0, v35, vcc
	v_add_co_u32_e32 v34, vcc, 0xf7000, v34
	v_addc_co_u32_e32 v35, vcc, 0, v35, vcc
	global_load_ushort v105, v[36:37], off offset:512
	global_load_ushort v106, v[38:39], off offset:1024
	global_load_ushort v107, v[38:39], off offset:2048
	global_load_ushort v108, v[40:41], off offset:1536
	global_load_ushort v109, v[34:35], off offset:3072
	s_nop 0
	global_load_ushort v41, v[40:41], off offset:2560
	s_nop 0
	global_load_ushort v40, v[36:37], off offset:1536
	global_load_ushort v110, v[34:35], off offset:2048
	s_waitcnt vmcnt(30)
	v_lshl_or_b32 v72, v79, 16, v78
	s_waitcnt vmcnt(27)
	v_lshl_or_b32 v73, v86, 16, v85
	s_waitcnt vmcnt(22)
	v_lshl_or_b32 v74, v91, 16, v90
	s_waitcnt vmcnt(19)
	v_lshl_or_b32 v75, v94, 16, v93
	v_lshl_or_b32 v34, v84, 16, v89
	v_lshl_or_b32 v35, v88, 16, v87
	s_waitcnt vmcnt(16)
	v_lshl_or_b32 v36, v92, 16, v97
	v_lshl_or_b32 v37, v95, 16, v96
	s_waitcnt vmcnt(14)
	v_lshl_or_b32 v76, v99, 16, v98
	s_waitcnt vmcnt(9)
	v_lshl_or_b32 v39, v104, 16, v103
	s_waitcnt vmcnt(8)
	v_lshl_or_b32 v38, v100, 16, v77
	v_lshl_or_b32 v77, v102, 16, v101
	s_waitcnt vmcnt(6)
	v_lshl_or_b32 v78, v106, 16, v105
	s_waitcnt vmcnt(2)
	v_lshl_or_b32 v41, v109, 16, v41
	s_waitcnt vmcnt(1)
	v_lshl_or_b32 v40, v107, 16, v40
	s_waitcnt vmcnt(0)
	v_lshl_or_b32 v79, v110, 16, v108

; template <bool OUT> DI void hgrn_item(LAS unsigned char* lds, bf16_t* proj, float* hst, float* hdv, const float* normw, int item, bool dry) {
;     ...
;     float* hs = hst + (size_t)item * 16384 + (size_t)(w * 8) * 256 + lane * 4;
;     if (OUT) {
; #pragma unroll
;         for (int i = 0; i < 8; ++i) st[i] = *(const f32x4*)(hs + i * 256);
;     } else {
; #pragma unroll
;         for (int i = 0; i < 8; ++i) st[i] = (f32x4){0.f, 0.f, 0.f, 0.f};
;     }
;     float btot = 0.f;
;     unsigned rg[8], rqv[8], rvv[8];
.LBB0_1169:
	s_lshl_b32 s14, s83, 1
	v_readfirstlane_b32 s21, v183
	s_ashr_i32 s17, s16, 31
	s_bfe_u32 s22, s40, 0x40008
	s_and_b32 s14, s14, 0x300
	s_and_b32 s85, s40, 0xf00
	s_lshr_b32 s20, s21, 6
	s_lshl_b64 s[18:19], s[16:17], 16
	s_add_u32 s17, s70, s18
	s_addc_u32 s23, s71, s19
	s_lshl_b32 s18, s20, 3
	s_mov_b32 s19, s15
	s_lshl_b64 s[18:19], s[18:19], 10
	s_add_u32 s18, s17, s18
	s_addc_u32 s19, s23, s19
	s_ashr_i32 s36, s16, 6
	s_ashr_i32 s37, s36, 31
	s_lshl_b32 s17, s16, 8
	s_lshl_b64 s[34:35], s[36:37], 12
	s_and_b32 s17, s17, 0xf00
	s_or_b32 s17, s34, s17
	v_or_b32_e32 v2, s17, v76
	v_mad_u64_u32 v[2:3], s[24:25], v2, s50, v[90:91]
	s_lshl_b32 s17, s16, 4
	v_mad_i32_i24 v3, s35, v114, v3
	s_and_b32 s24, s17, 0x300
	s_mov_b32 s25, s15
	v_lshl_add_u64 v[2:3], v[2:3], 0, s[24:25]
	v_lshl_add_u64 v[2:3], v[2:3], 0, v[88:89]
	v_add_co_u32_e32 v4, vcc, s51, v2
	v_lshl_add_u64 v[14:15], s[18:19], 0, v[74:75]
	s_nop 0
	v_addc_co_u32_e32 v5, vcc, 0, v3, vcc
	v_add_co_u32_e32 v6, vcc, s52, v2
	s_bfe_u32 s17, s21, 0x20006
	s_nop 0
	v_addc_co_u32_e32 v7, vcc, 0, v3, vcc
	v_add_co_u32_e32 v8, vcc, s53, v2
	s_and_b32 s86, s21, 0xffffffc0
	s_nop 0
	v_addc_co_u32_e32 v9, vcc, 0, v3, vcc
	global_load_ushort v184, v[2:3], off offset:2560
	global_load_ushort v185, v[4:5], off offset:3072
	global_load_ushort v186, v[2:3], off offset:3584
	global_load_ushort v187, v[6:7], off
	global_load_ushort v188, v[8:9], off offset:3584
	global_load_ushort v189, v[8:9], off offset:2560
	global_load_ushort v190, v[4:5], off offset:2048
	global_load_ushort v191, v[2:3], off offset:1536
	v_add_co_u32_e32 v4, vcc, s54, v2
	s_lshr_b32 s21, s21, 8
	s_nop 0
	v_addc_co_u32_e32 v5, vcc, 0, v3, vcc
	v_add_co_u32_e32 v6, vcc, s55, v2
	s_cmp_le_u32 s17, s21
	s_nop 0
	v_addc_co_u32_e32 v7, vcc, 0, v3, vcc
	v_add_co_u32_e32 v8, vcc, s58, v2
	s_mul_i32 s37, s22, 0x320000
	s_nop 0
	v_addc_co_u32_e32 v9, vcc, 0, v3, vcc
	v_add_co_u32_e32 v10, vcc, s59, v2
	v_lshl_or_b32 v120, s17, 4, v1
	s_nop 0
	v_addc_co_u32_e32 v11, vcc, 0, v3, vcc
	v_add_co_u32_e32 v12, vcc, s66, v2
	s_mul_hi_i32 s87, s36, 0x3200000
	s_nop 0
	v_addc_co_u32_e32 v13, vcc, 0, v3, vcc
	global_load_ushort v192, v[4:5], off
	global_load_ushort v193, v[6:7], off offset:512
	global_load_ushort v194, v[8:9], off offset:3072
	global_load_ushort v195, v[10:11], off offset:512
	global_load_ushort v196, v[12:13], off offset:1024
	global_load_ushort v197, v[10:11], off offset:1536
	global_load_ushort v198, v[12:13], off
	global_load_ushort v199, v[4:5], off offset:1024
	v_add_co_u32_e32 v4, vcc, s67, v2
	s_mul_i32 s36, s36, 0x3200000
	s_nop 0
	v_addc_co_u32_e32 v5, vcc, 0, v3, vcc
	v_add_co_u32_e32 v6, vcc, s68, v2
	v_add_u32_e32 v125, s86, v109
	s_nop 0
	v_addc_co_u32_e32 v7, vcc, 0, v3, vcc
	v_add_co_u32_e32 v8, vcc, s69, v2
	v_addc_co_u32_e32 v9, vcc, 0, v3, vcc
	global_load_ushort v200, v[12:13], off offset:2048
	global_load_ushort v201, v[4:5], off offset:3584
	global_load_ushort v202, v[6:7], off offset:1536
	global_load_ushort v203, v[8:9], off offset:2048
	global_load_ushort v204, v[6:7], off offset:2560
	global_load_ushort v205, v[8:9], off offset:3072
	global_load_ushort v206, v[8:9], off offset:1024
	global_load_ushort v207, v[6:7], off offset:512
	v_add_co_u32_e32 v4, vcc, s72, v2
	s_nop 0
	v_addc_co_u32_e32 v5, vcc, 0, v3, vcc
	v_add_co_u32_e32 v6, vcc, s73, v2
	s_nop 0
	v_addc_co_u32_e32 v7, vcc, 0, v3, vcc
	v_add_co_u32_e32 v8, vcc, s74, v2
	s_nop 0
	v_addc_co_u32_e32 v9, vcc, 0, v3, vcc
	v_add_co_u32_e32 v10, vcc, s75, v2
	s_nop 0
	v_addc_co_u32_e32 v11, vcc, 0, v3, vcc
	global_load_ushort v208, v[4:5], off offset:2560
	global_load_ushort v209, v[6:7], off offset:3072
	global_load_ushort v210, v[4:5], off offset:3584
	global_load_ushort v211, v[8:9], off
	global_load_ushort v212, v[10:11], off offset:3584
	global_load_ushort v213, v[10:11], off offset:2560
	global_load_ushort v214, v[6:7], off offset:2048
	global_load_ushort v215, v[4:5], off offset:1536
	v_add_co_u32_e32 v4, vcc, s76, v2
	s_nop 0
	v_addc_co_u32_e32 v5, vcc, 0, v3, vcc
	v_add_co_u32_e32 v6, vcc, s77, v2
	s_nop 0
	v_addc_co_u32_e32 v7, vcc, 0, v3, vcc
	v_add_co_u32_e32 v8, vcc, s78, v2
	s_nop 0
	v_addc_co_u32_e32 v9, vcc, 0, v3, vcc
	v_add_co_u32_e32 v10, vcc, s79, v2
	s_nop 0
	v_addc_co_u32_e32 v11, vcc, 0, v3, vcc
	v_add_co_u32_e32 v12, vcc, s80, v2
	s_nop 0
	v_addc_co_u32_e32 v13, vcc, 0, v3, vcc
	global_load_ushort v216, v[4:5], off
	global_load_ushort v217, v[6:7], off offset:512
	global_load_ushort v218, v[8:9], off offset:3072
	global_load_ushort v219, v[10:11], off offset:512
; #define LAS __attribute__((address_space(3)))
; DI float bflo(unsigned w) { return __uint_as_float(w << 16); }
; DI float bfhi(unsigned w) { return __uint_as_float(w & 0xffff0000u); }
; template <bool OUT> DI void hgrn_item(LAS unsigned char* lds, bf16_t* proj, float* hst, float* hdv, const float* normw, int item, bool dry) {
;     ...
;         for (int i = 0; i < 8; ++i) st[i] = *(const f32x4*)(hs + i * 256);
;     ...
;         for (int i = 0; i < 8; ++i) { gl[2 * i] = bflo(rg[i]); gl[2 * i + 1] = bfhi(rg[i]); if (OUT) { qv[2 * i] = bflo(rqv[i]); qv[2 * i + 1] = bfhi(rqv[i]); } }
;         *(LAS u32x4*)(VT + d * TP + tq * 16) = (u32x4){rvv[0], rvv[1], rvv[2], rvv[3]};
;         *(LAS u32x4*)(VT + d * TP + tq * 16 + 8) = (u32x4){rvv[4], rvv[5], rvv[6], rvv[7]};
	global_load_ushort v220, v[12:13], off offset:1024
	global_load_ushort v221, v[10:11], off offset:1536
	global_load_ushort v222, v[12:13], off
	global_load_ushort v223, v[4:5], off offset:1024
	v_add_co_u32_e32 v4, vcc, s81, v2
	s_nop 0
	v_addc_co_u32_e32 v5, vcc, 0, v3, vcc
	v_add_co_u32_e32 v6, vcc, s82, v2
	s_nop 0
	v_addc_co_u32_e32 v7, vcc, 0, v3, vcc
	v_add_co_u32_e32 v2, vcc, s84, v2
	v_addc_co_u32_e32 v3, vcc, 0, v3, vcc
	v_add_co_u32_e32 v30, vcc, s47, v14
	global_load_ushort v224, v[12:13], off offset:2048
	global_load_ushort v225, v[4:5], off offset:3584
	global_load_ushort v226, v[6:7], off offset:1536
	global_load_ushort v227, v[2:3], off offset:2048
	global_load_ushort v228, v[6:7], off offset:2560
	global_load_ushort v229, v[2:3], off offset:3072
	global_load_ushort v230, v[2:3], off offset:1024
	global_load_ushort v231, v[6:7], off offset:512
	v_addc_co_u32_e32 v31, vcc, 0, v15, vcc
	global_load_dwordx4 v[6:9], v74, s[18:19]
	global_load_dwordx4 v[10:13], v74, s[18:19] offset:1024
	global_load_dwordx4 v[2:5], v74, s[18:19] offset:2048
	global_load_dwordx4 v[18:21], v74, s[18:19] offset:3072
	global_load_dwordx4 v[14:17], v[30:31], off
	global_load_dwordx4 v[26:29], v[30:31], off offset:1024
	global_load_dwordx4 v[22:25], v[30:31], off offset:2048
	s_nop 0
	global_load_dwordx4 v[30:33], v[30:31], off offset:3072
	s_cselect_b64 s[18:19], -1, 0
	s_cmp_gt_u32 s17, s21
	v_lshl_or_b32 v58, s20, 4, v1
	s_cselect_b64 s[30:31], -1, 0
	s_add_i32 s20, s20, 8
	s_lshl_b32 s24, s21, 4
	s_lshr_b32 s25, s20, 2
	s_cmp_gt_u32 s17, s25
	s_cselect_b64 s[20:21], -1, 0
	s_cmp_le_u32 s17, s25
	s_cselect_b64 s[22:23], -1, 0
	s_lshl_b32 s17, s25, 4
	v_mul_lo_u32 v62, v58, s39
	v_or_b32_e32 v58, s24, v1
	v_mul_u32_u24_e32 v63, 0x110, v120
	v_add_u32_e32 v121, v93, v62
	v_add_u32_e32 v126, v105, v63
	v_mul_lo_u32 v64, v58, s38
	v_or_b32_e32 v58, s17, v1
	v_mul_lo_u32 v65, v58, s38
	v_or_b32_e32 v58, s24, v104
	v_cmp_gt_u32_e32 vcc, v120, v58
	v_or_b32_e32 v59, 1, v58
	s_or_b64 s[24:25], s[30:31], vcc
	v_cmp_gt_u32_e32 vcc, v120, v59
	v_or_b32_e32 v59, 2, v58
	v_mul_lo_u32 v66, v58, s39
	s_or_b64 s[26:27], s[30:31], vcc
	v_cmp_gt_u32_e32 vcc, v120, v59
	v_or_b32_e32 v58, 3, v58
	s_or_b64 s[28:29], s[30:31], vcc
	v_cmp_gt_u32_e32 vcc, v120, v58
	s_or_b64 s[30:31], s[30:31], vcc
	s_add_u32 s36, s36, s37
	v_or_b32_e32 v58, s34, v82
	s_addc_u32 s37, s87, 0
	s_or_b32 s36, s36, s14
	v_or_b32_e32 v60, s85, v58
	v_mov_b64_e32 v[58:59], s[14:15]
	v_add_u32_e32 v122, v105, v64
	v_add_u32_e32 v124, v105, v65
	v_lshl_add_u64 v[94:95], v[84:85], 0, s[36:37]
	v_mad_u64_u32 v[60:61], s[36:37], v60, s50, v[58:59]
	v_mad_i32_i24 v61, s35, v114, v61
	v_lshl_add_u64 v[96:97], v[86:87], 0, v[60:61]
	v_or_b32_e32 v60, s34, v80
	v_or_b32_e32 v60, s85, v60
	v_mad_u64_u32 v[58:59], s[36:37], v60, s50, v[58:59]
	v_lshl_add_u32 v92, v120, 1, s33
	v_mad_i32_i24 v59, s35, v114, v59
	v_lshl_add_u64 v[98:99], v[86:87], 0, v[58:59]
	s_mov_b64 s[34:35], 0
	v_add_u32_e32 v123, v92, v66
	s_waitcnt vmcnt(54)
	v_lshl_or_b32 v42, v185, 16, v184
	s_waitcnt vmcnt(52)
	v_lshl_or_b32 v34, v187, 16, v186
	s_waitcnt vmcnt(48)
	v_lshl_or_b32 v46, v190, 16, v191
	v_mov_b32_e32 v127, v46
	v_mov_b32_e32 v129, v42
	s_waitcnt vmcnt(47)
	v_lshl_or_b32 v43, v192, 16, v188
	s_waitcnt vmcnt(40)
	v_lshl_or_b32 v35, v199, 16, v193
	v_lshl_or_b32 v44, v196, 16, v195
	v_lshl_or_b32 v47, v194, 16, v189
	v_mov_b32_e32 v128, v47
	v_mov_b32_e32 v131, v43
	v_mov_b32_e32 v133, v44
	s_waitcnt vmcnt(39)
	v_lshl_or_b32 v36, v200, 16, v197
	s_waitcnt vmcnt(38)
	v_lshl_or_b32 v49, v198, 16, v201
	s_waitcnt vmcnt(32)
	v_lshl_or_b32 v51, v206, 16, v207
	s_waitcnt vmcnt(28)
	v_lshl_or_b32 v38, v211, 16, v210
	v_lshl_or_b32 v45, v203, 16, v202
	s_waitcnt vmcnt(24)
	v_lshl_or_b32 v52, v214, 16, v215
	v_lshl_or_b32 v50, v209, 16, v208
	v_lshl_or_b32 v37, v205, 16, v204
	v_mov_b32_e32 v130, v49
	v_mov_b32_e32 v132, v51
	v_mov_b32_e32 v134, v52
	v_mov_b32_e32 v135, v45
	v_mov_b32_e32 v137, v50
	s_waitcnt vmcnt(23)
	v_lshl_or_b32 v55, v216, 16, v212
	s_waitcnt vmcnt(21)
	v_lshl_or_b32 v53, v218, 16, v213
	s_waitcnt vmcnt(16)
	v_lshl_or_b32 v39, v223, 16, v217
	v_lshl_or_b32 v56, v220, 16, v219
	v_mov_b32_e32 v136, v53
	v_mov_b32_e32 v139, v55
	v_mov_b32_e32 v141, v56
	s_waitcnt vmcnt(15)
	v_lshl_or_b32 v40, v224, 16, v221
	s_waitcnt vmcnt(14)
	v_lshl_or_b32 v54, v222, 16, v225
	s_waitcnt vmcnt(12)
	v_lshl_or_b32 v57, v227, 16, v226
	s_waitcnt vmcnt(8)
	v_lshl_or_b32 v48, v230, 16, v231
	v_lshl_or_b32 v41, v229, 16, v228
	v_mov_b32_e32 v138, v54
	v_mov_b32_e32 v140, v48
	v_mov_b32_e32 v142, v57
	s_branch .LBB0_1171
